# code placement: one s_nop puts the three hand-written attention loops that sat at 4 mod 8 bytes on a 0 mod 8 phase
# baseline (speedup 1.0000x reference)
.LBB0_768:
	s_waitcnt vmcnt(0) lgkmcnt(0)
	s_mov_b32 s79, 0x3e38aa3b
	s_mov_b32 s77, 0xc000
	s_mov_b32 s78, 0xffffc000
	v_readlane_b32 s1, v253, 23
	v_readfirstlane_b32 s0, v170
	s_nop 3
	s_lshr_b32 s0, s0, 6
	s_and_b32 s74, s1, 7
	s_lshl_b32 s74, s74, 5
	s_lshr_b32 s75, s1, 3
	s_add_u32 s74, s74, s75
	s_lshl_b32 s74, s74, 3
	s_and_b32 s4, s74, 31
	s_lshr_b32 s75, s74, 5
	s_and_b32 s5, s75, 0
	s_lshr_b32 s75, s75, 0
	s_and_b32 s3, s75, 3
	s_lshr_b32 s2, s75, 2
	s_sub_u32 s6, 8, s0
	s_lshl_b32 s70, s0, 10
	s_lshl_b32 s74, s2, 21
	s_lshl_b32 s75, s3, 19
	s_add_u32 s74, s74, s75
	s_add_u32 s34, s40, s74
	s_addc_u32 s35, s41, 0
	s_mov_b32 s30, s34
	s_mov_b32 s31, s35
	s_lshl_b32 s74, s2, 16
	s_lshl_b32 s75, s3, 14
	s_add_u32 s74, s74, s75
	s_add_u32 s74, s74, 0xc000000
	s_add_u32 s58, s42, s74
	s_addc_u32 s59, s43, 0
	s_add_u32 s74, s2, 0
	s_lshl_b32 s74, s74, 2
	s_add_u32 s74, s74, s3
	s_lshl_b32 s74, s74, 19
	s_add_u32 s60, s42, s74
	s_addc_u32 s61, s43, 0
	s_lshl_b32 s74, s2, 6
	s_add_u32 s74, s74, 0
	s_lshl_b32 s74, s74, 15
	s_lshl_b32 s75, s3, 13
	s_add_u32 s74, s74, s75
	s_add_u32 s74, s74, 0x6000000
	s_add_u32 s64, s42, s74
	s_addc_u32 s65, s43, 0
	v_and_b32_e32 v141, 63, v170
	v_and_b32_e32 v241, 15, v141
	v_lshrrev_b32_e32 v242, 4, v141
	v_mov_b32_e32 v244, 0xf149f2ca
	v_mov_b32_e32 v248, 0
	v_mov_b32_e32 v249, 0
	v_lshrrev_b32_e32 v142, 1, v241
	v_xor_b32_e32 v142, v142, v242
	v_lshlrev_b32_e32 v142, 4, v142
	v_lshl_add_u32 v142, v241, 7, v142
	s_lshl_b32 s74, s0, 11
	v_add_u32_e32 v230, s74, v142
	v_xor_b32_e32 v231, 64, v230
	v_lshrrev_b32_e32 v142, 1, v242
	v_xor_b32_e32 v243, v142, v241
	v_and_b32_e32 v142, 1, v242
	v_lshlrev_b32_e32 v142, 3, v142
	v_lshl_add_u32 v142, v241, 8, v142
	v_add_u32_e32 v142, 0x10000, v142
	s_add_u32 s74, s0, 0
	s_and_b32 s75, s74, 7
	s_lshl_b32 s75, s75, 1
	s_lshr_b32 s74, s74, 3
	s_lshl_b32 s74, s74, 14
	v_xor_b32_e32 v143, s75, v243
	v_lshl_add_u32 v143, v143, 4, v142
	v_add_u32_e32 v221, s74, v143
	s_add_u32 s74, s0, 1
	s_and_b32 s75, s74, 7
	s_lshl_b32 s75, s75, 1
	s_lshr_b32 s74, s74, 3
	s_lshl_b32 s74, s74, 14
	v_xor_b32_e32 v143, s75, v243
	v_lshl_add_u32 v143, v143, 4, v142
	v_add_u32_e32 v222, s74, v143
	s_add_u32 s74, s0, 2
	s_and_b32 s75, s74, 7
	s_lshl_b32 s75, s75, 1
	s_lshr_b32 s74, s74, 3
	s_lshl_b32 s74, s74, 14
	v_xor_b32_e32 v143, s75, v243
	v_lshl_add_u32 v143, v143, 4, v142
	v_add_u32_e32 v223, s74, v143
	s_add_u32 s74, s0, 3
	s_and_b32 s75, s74, 7
	s_lshl_b32 s75, s75, 1
	s_lshr_b32 s74, s74, 3
	s_lshl_b32 s74, s74, 14
	v_xor_b32_e32 v143, s75, v243
	v_lshl_add_u32 v143, v143, 4, v142
	v_add_u32_e32 v224, s74, v143
	s_add_u32 s74, s0, 4
	s_and_b32 s75, s74, 7
	s_lshl_b32 s75, s75, 1
	s_lshr_b32 s74, s74, 3
	s_lshl_b32 s74, s74, 14
	v_xor_b32_e32 v143, s75, v243
	v_lshl_add_u32 v143, v143, 4, v142
	v_add_u32_e32 v225, s74, v143
	s_add_u32 s74, s0, 5
	s_and_b32 s75, s74, 7
	s_lshl_b32 s75, s75, 1
	s_lshr_b32 s74, s74, 3
	s_lshl_b32 s74, s74, 14
	v_xor_b32_e32 v143, s75, v243
	v_lshl_add_u32 v143, v143, 4, v142
	v_add_u32_e32 v226, s74, v143
	s_add_u32 s74, s0, 6
	s_and_b32 s75, s74, 7
	s_lshl_b32 s75, s75, 1
	s_lshr_b32 s74, s74, 3
	s_lshl_b32 s74, s74, 14
	v_xor_b32_e32 v143, s75, v243
	v_lshl_add_u32 v143, v143, 4, v142
	v_add_u32_e32 v227, s74, v143
	s_add_u32 s74, s0, 7
	s_and_b32 s75, s74, 7
	s_lshl_b32 s75, s75, 1
	s_lshr_b32 s74, s74, 3
	s_lshl_b32 s74, s74, 14
	v_xor_b32_e32 v143, s75, v243
	v_lshl_add_u32 v143, v143, 4, v142
	v_add_u32_e32 v228, s74, v143
	s_add_u32 s74, s0, 8
	s_and_b32 s75, s74, 7
	s_lshl_b32 s75, s75, 1
	s_lshr_b32 s74, s74, 3
	s_lshl_b32 s74, s74, 14
	v_xor_b32_e32 v143, s75, v243
	v_lshl_add_u32 v143, v143, 4, v142
	v_add_u32_e32 v229, s74, v143
	s_and_b32 s74, s0, 1
	s_lshl_b32 s74, s74, 2
	v_add_u32_e32 v142, s74, v242
	v_and_b32_e32 v143, 7, v141
	v_xor_b32_e32 v142, v142, v143
	v_lshlrev_b32_e32 v142, 4, v142
	v_lshrrev_b32_e32 v143, 3, v141
	s_lshl_b32 s74, s0, 3
	v_add_u32_e32 v143, s74, v143
	v_lshl_add_u32 v232, v143, 7, v142
	v_add_u32_e32 v233, 0x2000, v232
	s_and_b32 s74, s0, 3
	s_lshl_b32 s74, s74, 2
	v_add_u32_e32 v142, s74, v242
	v_xor_b32_e32 v142, v142, v241
	v_lshlrev_b32_e32 v142, 4, v142
	s_lshl_b32 s74, s0, 2
	v_add_u32_e32 v143, s74, v242
	v_lshl_add_u32 v234, v143, 15, v142
	v_add_u32_e32 v235, 0x100000, v234
	s_lshl_b32 s74, s0, 4
	v_add_u32_e32 v142, s74, v241
	v_lshlrev_b32_e32 v142, 0, v142
	v_lshlrev_b32_e32 v238, 2, v142
	v_lshlrev_b32_e32 v142, 7, v142
	v_lshl_add_u32 v236, v242, 4, v142
	v_lshl_add_u32 v237, v242, 3, v142
	v_xor_b32_e32 v142, 16, v141
	v_lshlrev_b32_e32 v239, 2, v142
	v_xor_b32_e32 v142, 32, v141
	v_lshlrev_b32_e32 v240, 2, v142
	s_add_u32 s74, s2, 1
	v_cvt_f32_u32_e32 v142, s74
	v_mul_f32_e32 v142, 0xc1000000, v142
	v_mul_f32_e32 v142, 0x3caaaaab, v142
	v_exp_f32_e32 v142, v142
	v_lshlrev_b32_e32 v144, 2, v242
	v_sub_u32_e32 v145, v241, v144
	v_mul_f32_e32 v142, 0x3f800000, v142
	v_add_u32_e32 v145, 0x80, v145
	v_mul_f32_e32 v142, 0x3fb8aa3b, v142
	v_cvt_f32_i32_e32 v145, v145
	s_nop 0
	v_mul_f32_e64 v143, -v142, v145
	v_fmamk_f32 v185, v142, 0x0, v143
	v_fmamk_f32 v186, v142, 0x3f800000, v143
	v_fmamk_f32 v187, v142, 0x40000000, v143
	v_fmamk_f32 v188, v142, 0x40400000, v143
	v_fmamk_f32 v189, v142, 0x41800000, v143
	v_fmamk_f32 v190, v142, 0x41880000, v143
	v_fmamk_f32 v191, v142, 0x41900000, v143
	v_fmamk_f32 v192, v142, 0x41980000, v143
	v_fmamk_f32 v193, v142, 0x42000000, v143
	v_fmamk_f32 v194, v142, 0x42040000, v143
	v_fmamk_f32 v195, v142, 0x42080000, v143
	v_fmamk_f32 v196, v142, 0x420c0000, v143
	v_fmamk_f32 v197, v142, 0x42400000, v143
	v_fmamk_f32 v198, v142, 0x42440000, v143
	v_fmamk_f32 v199, v142, 0x42480000, v143
	v_fmamk_f32 v200, v142, 0x424c0000, v143
	v_fmamk_f32 v201, v142, 0x42800000, v143
	v_fmamk_f32 v202, v142, 0x42820000, v143
	v_fmamk_f32 v203, v142, 0x42840000, v143
	v_fmamk_f32 v204, v142, 0x42860000, v143
	v_fmamk_f32 v205, v142, 0x42a00000, v143
	v_fmamk_f32 v206, v142, 0x42a20000, v143
	v_fmamk_f32 v207, v142, 0x42a40000, v143
	v_fmamk_f32 v208, v142, 0x42a60000, v143
	v_fmamk_f32 v209, v142, 0x42c00000, v143
	v_fmamk_f32 v210, v142, 0x42c20000, v143
	v_fmamk_f32 v211, v142, 0x42c40000, v143
	v_fmamk_f32 v212, v142, 0x42c60000, v143
	v_fmamk_f32 v213, v142, 0x42e00000, v143
	v_fmamk_f32 v214, v142, 0x42e20000, v143
	v_fmamk_f32 v215, v142, 0x42e40000, v143
	v_fmamk_f32 v216, v142, 0x42e60000, v143
	v_fmamk_f32 v217, v142, 0x43000000, v143
	v_fmamk_f32 v218, v142, 0x43010000, v143
	v_fmamk_f32 v219, v142, 0x43020000, v143
	v_fmamk_f32 v220, v142, 0x43030000, v143
	v_add_u32_e32 v145, 0, v144
	v_cmp_lt_u32_e32 vcc, v145, v241
	s_nop 1
	v_cndmask_b32_e32 v185, v185, v244, vcc
	v_cmp_gt_u32_e32 vcc, v145, v241
	s_nop 1
	v_cndmask_b32_e32 v217, v217, v244, vcc
	v_add_u32_e32 v145, 1, v144
	v_cmp_lt_u32_e32 vcc, v145, v241
	s_nop 1
	v_cndmask_b32_e32 v186, v186, v244, vcc
	v_cmp_gt_u32_e32 vcc, v145, v241
	s_nop 1
	v_cndmask_b32_e32 v218, v218, v244, vcc
	v_add_u32_e32 v145, 2, v144
	v_cmp_lt_u32_e32 vcc, v145, v241
	s_nop 1
	v_cndmask_b32_e32 v187, v187, v244, vcc
	v_cmp_gt_u32_e32 vcc, v145, v241
	s_nop 1
	v_cndmask_b32_e32 v219, v219, v244, vcc
	v_add_u32_e32 v145, 3, v144
	v_cmp_lt_u32_e32 vcc, v145, v241
	s_nop 1
	v_cndmask_b32_e32 v188, v188, v244, vcc
	v_cmp_gt_u32_e32 vcc, v145, v241
	s_nop 1
	v_cndmask_b32_e32 v220, v220, v244, vcc
	s_lshl_b32 s74, s4, 7
	s_add_u32 s74, s74, s5
	s_lshl_b32 s75, s74, 7
	s_add_u32 s10, s30, s75
	s_addc_u32 s11, s31, 0
	s_add_u32 s86, s34, s75
	s_addc_u32 s87, s35, 0
	s_lshl_b32 s75, s74, 2
	s_add_u32 s88, s58, s75
	s_addc_u32 s89, s59, 0
	global_load_dwordx4 v[96:99], v236, s[10:11]
	global_load_dwordx4 v[100:103], v236, s[10:11] offset:64
	s_mov_b32 s7, 0
	s_nop 0
